# out-projection epilogue: the four g_pre vectors fetched once before the H-store loop instead of one load plus vmcnt(0) per piece
# speedup vs baseline: 1.0166x; 1.0084x over previous
.LBB0_1334:
	s_or_b64 exec, exec, s[8:9]
	s_lshl_b32 s6, s86, 11
	s_addk_i32 s6, 0x800
	s_waitcnt lgkmcnt(0)
	s_barrier
	v_add_u32_e32 v128, 0x1000, v249
	s_and_b64 s[4:5], exec, s[4:5]
	ds_read2_b32 v[134:135], v128 offset1:16
	s_cselect_b32 s26, 0, s6
	s_lshl_b64 s[4:5], s[26:27], 2
	s_add_u32 s6, s80, s4
	s_addc_u32 s7, s81, s5
	s_waitcnt lgkmcnt(0)
	v_pk_mul_f32 v[138:139], v[124:125], v[134:135] op_sel_hi:[1,0]
	v_lshl_add_u64 v[124:125], v[212:213], 2, s[6:7]
	global_load_dwordx4 v[140:143], v[124:125], off
	global_load_dwordx4 v[144:147], v[124:125], off offset:64
	global_load_dwordx4 v[148:151], v[124:125], off offset:512
	global_load_dwordx4 v[152:155], v[124:125], off offset:576
	s_waitcnt vmcnt(0)
	v_mov_b64_e32 v[130:131], v[140:141]
	v_mov_b64_e32 v[132:133], v[142:143]
	s_add_u32 s4, s56, 0x9400000
	v_pk_mul_f32 v[126:127], v[126:127], v[134:135] op_sel_hi:[1,0]
	s_addc_u32 s5, s57, 0
	v_lshlrev_b64 v[136:137], 12, v[224:225]
	s_waitcnt vmcnt(0)
	v_pk_mul_f32 v[126:127], v[132:133], v[126:127]
	v_pk_mul_f32 v[130:131], v[130:131], v[138:139]
	v_lshl_add_u64 v[132:133], s[4:5], 0, v[136:137]
	v_cvt_pk_bf16_f32 v130, v130, v131
	v_cvt_pk_bf16_f32 v131, v126, v127
	v_lshlrev_b64 v[126:127], 1, v[212:213]
	v_lshl_add_u64 v[132:133], v[132:133], 0, v[126:127]
	global_store_dwordx2 v[132:133], v[130:131], off
	v_pk_mul_f32 v[130:131], v[122:123], v[134:135] op_sel_hi:[1,0]
	v_pk_mul_f32 v[136:137], v[120:121], v[134:135] op_sel_hi:[1,0]
	v_mov_b64_e32 v[120:121], v[144:145]
	v_mov_b64_e32 v[122:123], v[146:147]
	v_pk_mul_f32 v[122:123], v[130:131], v[122:123]
	v_pk_mul_f32 v[120:121], v[136:137], v[120:121]
	s_nop 0
	v_cvt_pk_bf16_f32 v120, v120, v121
	v_cvt_pk_bf16_f32 v121, v122, v123
	global_store_dwordx2 v[132:133], v[120:121], off offset:32
	v_pk_mul_f32 v[120:121], v[118:119], v[134:135] op_sel_hi:[1,0]
	v_pk_mul_f32 v[122:123], v[116:117], v[134:135] op_sel_hi:[1,0]
	v_mov_b64_e32 v[116:117], v[148:149]
	v_mov_b64_e32 v[118:119], v[150:151]
	v_pk_mul_f32 v[118:119], v[120:121], v[118:119]
	v_pk_mul_f32 v[116:117], v[122:123], v[116:117]
	s_nop 0
	v_cvt_pk_bf16_f32 v116, v116, v117
	v_cvt_pk_bf16_f32 v117, v118, v119
	global_store_dwordx2 v[132:133], v[116:117], off offset:256
	v_pk_mul_f32 v[116:117], v[114:115], v[134:135] op_sel_hi:[1,0]
	v_pk_mul_f32 v[118:119], v[112:113], v[134:135] op_sel_hi:[1,0]
	v_mov_b64_e32 v[112:113], v[152:153]
	v_mov_b64_e32 v[114:115], v[154:155]
	v_pk_mul_f32 v[114:115], v[116:117], v[114:115]
	v_pk_mul_f32 v[112:113], v[118:119], v[112:113]
	s_nop 0
	v_cvt_pk_bf16_f32 v112, v112, v113
	v_cvt_pk_bf16_f32 v113, v114, v115
	global_store_dwordx2 v[132:133], v[112:113], off offset:288
	v_mov_b32_e32 v114, v135
	v_pk_mul_f32 v[116:117], v[110:111], v[114:115] op_sel_hi:[1,0]
	v_pk_mul_f32 v[118:119], v[108:109], v[114:115] op_sel_hi:[1,0]
	v_mov_b64_e32 v[108:109], v[140:141]
	v_mov_b64_e32 v[110:111], v[142:143]
	v_lshlrev_b64 v[112:113], 12, v[222:223]
	v_pk_mul_f32 v[110:111], v[110:111], v[116:117]
	v_pk_mul_f32 v[108:109], v[108:109], v[118:119]
	s_nop 0
	v_cvt_pk_bf16_f32 v108, v108, v109
	v_cvt_pk_bf16_f32 v109, v110, v111
	v_lshl_add_u64 v[110:111], s[4:5], 0, v[112:113]
	v_lshl_add_u64 v[110:111], v[110:111], 0, v[126:127]
	global_store_dwordx2 v[110:111], v[108:109], off
	v_pk_mul_f32 v[108:109], v[106:107], v[114:115] op_sel_hi:[1,0]
	v_pk_mul_f32 v[112:113], v[104:105], v[114:115] op_sel_hi:[1,0]
	v_mov_b64_e32 v[104:105], v[144:145]
	v_mov_b64_e32 v[106:107], v[146:147]
	v_pk_mul_f32 v[106:107], v[108:109], v[106:107]
	v_pk_mul_f32 v[104:105], v[112:113], v[104:105]
	s_nop 0
	v_cvt_pk_bf16_f32 v104, v104, v105
	v_cvt_pk_bf16_f32 v105, v106, v107
	global_store_dwordx2 v[110:111], v[104:105], off offset:32
	v_pk_mul_f32 v[104:105], v[102:103], v[114:115] op_sel_hi:[1,0]
	v_pk_mul_f32 v[106:107], v[100:101], v[114:115] op_sel_hi:[1,0]
	v_mov_b64_e32 v[100:101], v[148:149]
	v_mov_b64_e32 v[102:103], v[150:151]
	v_pk_mul_f32 v[102:103], v[104:105], v[102:103]
	v_pk_mul_f32 v[100:101], v[106:107], v[100:101]
	s_nop 0
	v_cvt_pk_bf16_f32 v100, v100, v101
	v_cvt_pk_bf16_f32 v101, v102, v103
	global_store_dwordx2 v[110:111], v[100:101], off offset:256
	v_pk_mul_f32 v[100:101], v[98:99], v[114:115] op_sel_hi:[1,0]
	v_pk_mul_f32 v[102:103], v[96:97], v[114:115] op_sel_hi:[1,0]
	v_mov_b64_e32 v[96:97], v[152:153]
	v_mov_b64_e32 v[98:99], v[154:155]
	v_pk_mul_f32 v[98:99], v[100:101], v[98:99]
	v_pk_mul_f32 v[96:97], v[102:103], v[96:97]
	s_nop 0
	v_cvt_pk_bf16_f32 v96, v96, v97
	v_cvt_pk_bf16_f32 v97, v98, v99
	global_store_dwordx2 v[110:111], v[96:97], off offset:288
	ds_read2_b32 v[96:97], v128 offset0:32 offset1:48
	v_lshlrev_b64 v[98:99], 12, v[220:221]
	s_waitcnt lgkmcnt(0)
	v_pk_mul_f32 v[100:101], v[94:95], v[96:97] op_sel_hi:[1,0]
	v_pk_mul_f32 v[102:103], v[92:93], v[96:97] op_sel_hi:[1,0]
	v_mov_b64_e32 v[92:93], v[140:141]
	v_mov_b64_e32 v[94:95], v[142:143]
	v_pk_mul_f32 v[94:95], v[94:95], v[100:101]
	v_pk_mul_f32 v[92:93], v[92:93], v[102:103]
	s_nop 0
	v_cvt_pk_bf16_f32 v92, v92, v93
	v_cvt_pk_bf16_f32 v93, v94, v95
	v_lshl_add_u64 v[94:95], s[4:5], 0, v[98:99]
	v_lshl_add_u64 v[94:95], v[94:95], 0, v[126:127]
	global_store_dwordx2 v[94:95], v[92:93], off
	v_pk_mul_f32 v[92:93], v[90:91], v[96:97] op_sel_hi:[1,0]
	v_pk_mul_f32 v[98:99], v[88:89], v[96:97] op_sel_hi:[1,0]
	v_mov_b64_e32 v[88:89], v[144:145]
	v_mov_b64_e32 v[90:91], v[146:147]
	v_pk_mul_f32 v[90:91], v[92:93], v[90:91]
	v_pk_mul_f32 v[88:89], v[98:99], v[88:89]
	s_nop 0
	v_cvt_pk_bf16_f32 v88, v88, v89
	v_cvt_pk_bf16_f32 v89, v90, v91
	global_store_dwordx2 v[94:95], v[88:89], off offset:32
	v_pk_mul_f32 v[88:89], v[86:87], v[96:97] op_sel_hi:[1,0]
	v_pk_mul_f32 v[90:91], v[84:85], v[96:97] op_sel_hi:[1,0]
	v_mov_b64_e32 v[84:85], v[148:149]
	v_mov_b64_e32 v[86:87], v[150:151]
	v_pk_mul_f32 v[86:87], v[88:89], v[86:87]
	v_pk_mul_f32 v[84:85], v[90:91], v[84:85]
	s_nop 0
	v_cvt_pk_bf16_f32 v84, v84, v85
	v_cvt_pk_bf16_f32 v85, v86, v87
	global_store_dwordx2 v[94:95], v[84:85], off offset:256
	v_pk_mul_f32 v[84:85], v[82:83], v[96:97] op_sel_hi:[1,0]
	v_pk_mul_f32 v[86:87], v[80:81], v[96:97] op_sel_hi:[1,0]
	v_mov_b64_e32 v[80:81], v[152:153]
	v_mov_b64_e32 v[82:83], v[154:155]
	v_pk_mul_f32 v[82:83], v[84:85], v[82:83]
	v_pk_mul_f32 v[80:81], v[86:87], v[80:81]
	s_nop 0
	v_cvt_pk_bf16_f32 v80, v80, v81
	v_cvt_pk_bf16_f32 v81, v82, v83
	global_store_dwordx2 v[94:95], v[80:81], off offset:288
	v_mov_b32_e32 v82, v97
	v_pk_mul_f32 v[84:85], v[78:79], v[82:83] op_sel_hi:[1,0]
	v_pk_mul_f32 v[86:87], v[76:77], v[82:83] op_sel_hi:[1,0]
	v_mov_b64_e32 v[76:77], v[140:141]
	v_mov_b64_e32 v[78:79], v[142:143]
	v_lshlrev_b64 v[80:81], 12, v[218:219]
	v_pk_mul_f32 v[78:79], v[78:79], v[84:85]
	v_pk_mul_f32 v[76:77], v[76:77], v[86:87]
	s_nop 0
	v_cvt_pk_bf16_f32 v76, v76, v77
	v_cvt_pk_bf16_f32 v77, v78, v79
	v_lshl_add_u64 v[78:79], s[4:5], 0, v[80:81]
	v_lshl_add_u64 v[78:79], v[78:79], 0, v[126:127]
	global_store_dwordx2 v[78:79], v[76:77], off
	v_pk_mul_f32 v[76:77], v[74:75], v[82:83] op_sel_hi:[1,0]
	v_pk_mul_f32 v[80:81], v[72:73], v[82:83] op_sel_hi:[1,0]
	v_mov_b64_e32 v[72:73], v[144:145]
	v_mov_b64_e32 v[74:75], v[146:147]
	v_pk_mul_f32 v[74:75], v[76:77], v[74:75]
	v_pk_mul_f32 v[72:73], v[80:81], v[72:73]
	s_nop 0
	v_cvt_pk_bf16_f32 v72, v72, v73
	v_cvt_pk_bf16_f32 v73, v74, v75
	global_store_dwordx2 v[78:79], v[72:73], off offset:32
	v_pk_mul_f32 v[72:73], v[70:71], v[82:83] op_sel_hi:[1,0]
	v_pk_mul_f32 v[74:75], v[68:69], v[82:83] op_sel_hi:[1,0]
	v_mov_b64_e32 v[68:69], v[148:149]
	v_mov_b64_e32 v[70:71], v[150:151]
	v_pk_mul_f32 v[70:71], v[72:73], v[70:71]
	v_pk_mul_f32 v[68:69], v[74:75], v[68:69]
	s_nop 0
	v_cvt_pk_bf16_f32 v68, v68, v69
	v_cvt_pk_bf16_f32 v69, v70, v71
	global_store_dwordx2 v[78:79], v[68:69], off offset:256
	v_pk_mul_f32 v[68:69], v[66:67], v[82:83] op_sel_hi:[1,0]
	v_pk_mul_f32 v[70:71], v[64:65], v[82:83] op_sel_hi:[1,0]
	v_mov_b64_e32 v[64:65], v[152:153]
	v_mov_b64_e32 v[66:67], v[154:155]
	v_pk_mul_f32 v[66:67], v[68:69], v[66:67]
	v_pk_mul_f32 v[64:65], v[70:71], v[64:65]
	s_nop 0
	v_cvt_pk_bf16_f32 v64, v64, v65
	v_cvt_pk_bf16_f32 v65, v66, v67
	global_store_dwordx2 v[78:79], v[64:65], off offset:288
	ds_read2_b32 v[64:65], v128 offset0:128 offset1:144
	v_lshlrev_b64 v[66:67], 12, v[216:217]
	s_waitcnt lgkmcnt(0)
	v_pk_mul_f32 v[68:69], v[62:63], v[64:65] op_sel_hi:[1,0]
	v_pk_mul_f32 v[70:71], v[60:61], v[64:65] op_sel_hi:[1,0]
	v_mov_b64_e32 v[60:61], v[140:141]
	v_mov_b64_e32 v[62:63], v[142:143]
	v_pk_mul_f32 v[62:63], v[62:63], v[68:69]
	v_pk_mul_f32 v[60:61], v[60:61], v[70:71]
	s_nop 0
	v_cvt_pk_bf16_f32 v60, v60, v61
	v_cvt_pk_bf16_f32 v61, v62, v63
	v_lshl_add_u64 v[62:63], s[4:5], 0, v[66:67]
	v_lshl_add_u64 v[62:63], v[62:63], 0, v[126:127]
	global_store_dwordx2 v[62:63], v[60:61], off
	v_pk_mul_f32 v[60:61], v[58:59], v[64:65] op_sel_hi:[1,0]
	v_pk_mul_f32 v[66:67], v[56:57], v[64:65] op_sel_hi:[1,0]
	v_mov_b64_e32 v[56:57], v[144:145]
	v_mov_b64_e32 v[58:59], v[146:147]
	v_pk_mul_f32 v[58:59], v[60:61], v[58:59]
	v_pk_mul_f32 v[56:57], v[66:67], v[56:57]
	s_nop 0
	v_cvt_pk_bf16_f32 v56, v56, v57
	v_cvt_pk_bf16_f32 v57, v58, v59
	global_store_dwordx2 v[62:63], v[56:57], off offset:32
	v_pk_mul_f32 v[56:57], v[54:55], v[64:65] op_sel_hi:[1,0]
	v_pk_mul_f32 v[58:59], v[52:53], v[64:65] op_sel_hi:[1,0]
	v_mov_b64_e32 v[52:53], v[148:149]
	v_mov_b64_e32 v[54:55], v[150:151]
	v_pk_mul_f32 v[54:55], v[56:57], v[54:55]
	v_pk_mul_f32 v[52:53], v[58:59], v[52:53]
	s_nop 0
	v_cvt_pk_bf16_f32 v52, v52, v53
	v_cvt_pk_bf16_f32 v53, v54, v55
	global_store_dwordx2 v[62:63], v[52:53], off offset:256
	v_pk_mul_f32 v[52:53], v[50:51], v[64:65] op_sel_hi:[1,0]
	v_pk_mul_f32 v[54:55], v[48:49], v[64:65] op_sel_hi:[1,0]
	v_mov_b64_e32 v[48:49], v[152:153]
	v_mov_b64_e32 v[50:51], v[154:155]
	v_pk_mul_f32 v[50:51], v[52:53], v[50:51]
	v_pk_mul_f32 v[48:49], v[54:55], v[48:49]
	s_nop 0
	v_cvt_pk_bf16_f32 v48, v48, v49
	v_cvt_pk_bf16_f32 v49, v50, v51
	global_store_dwordx2 v[62:63], v[48:49], off offset:288
	v_mov_b32_e32 v50, v65
	v_pk_mul_f32 v[52:53], v[46:47], v[50:51] op_sel_hi:[1,0]
	v_pk_mul_f32 v[54:55], v[44:45], v[50:51] op_sel_hi:[1,0]
	v_mov_b64_e32 v[44:45], v[140:141]
	v_mov_b64_e32 v[46:47], v[142:143]
	v_lshlrev_b64 v[48:49], 12, v[192:193]
	v_pk_mul_f32 v[46:47], v[46:47], v[52:53]
	v_pk_mul_f32 v[44:45], v[44:45], v[54:55]
	s_nop 0
	v_cvt_pk_bf16_f32 v44, v44, v45
	v_cvt_pk_bf16_f32 v45, v46, v47
	v_lshl_add_u64 v[46:47], s[4:5], 0, v[48:49]
	v_lshl_add_u64 v[46:47], v[46:47], 0, v[126:127]
	global_store_dwordx2 v[46:47], v[44:45], off
	v_pk_mul_f32 v[44:45], v[42:43], v[50:51] op_sel_hi:[1,0]
	v_pk_mul_f32 v[48:49], v[40:41], v[50:51] op_sel_hi:[1,0]
	v_mov_b64_e32 v[40:41], v[144:145]
	v_mov_b64_e32 v[42:43], v[146:147]
	v_pk_mul_f32 v[42:43], v[44:45], v[42:43]
	v_pk_mul_f32 v[40:41], v[48:49], v[40:41]
	s_nop 0
	v_cvt_pk_bf16_f32 v40, v40, v41
	v_cvt_pk_bf16_f32 v41, v42, v43
	global_store_dwordx2 v[46:47], v[40:41], off offset:32
	v_pk_mul_f32 v[40:41], v[38:39], v[50:51] op_sel_hi:[1,0]
	v_pk_mul_f32 v[42:43], v[36:37], v[50:51] op_sel_hi:[1,0]
	v_mov_b64_e32 v[36:37], v[148:149]
	v_mov_b64_e32 v[38:39], v[150:151]
	v_pk_mul_f32 v[38:39], v[40:41], v[38:39]
	v_pk_mul_f32 v[36:37], v[42:43], v[36:37]
	s_nop 0
	v_cvt_pk_bf16_f32 v36, v36, v37
	v_cvt_pk_bf16_f32 v37, v38, v39
	global_store_dwordx2 v[46:47], v[36:37], off offset:256
	v_pk_mul_f32 v[36:37], v[34:35], v[50:51] op_sel_hi:[1,0]
	v_pk_mul_f32 v[38:39], v[32:33], v[50:51] op_sel_hi:[1,0]
	v_mov_b64_e32 v[32:33], v[152:153]
	v_mov_b64_e32 v[34:35], v[154:155]
	v_pk_mul_f32 v[34:35], v[36:37], v[34:35]
	v_pk_mul_f32 v[32:33], v[38:39], v[32:33]
	s_nop 0
	v_cvt_pk_bf16_f32 v32, v32, v33
	v_cvt_pk_bf16_f32 v33, v34, v35
	global_store_dwordx2 v[46:47], v[32:33], off offset:288
	ds_read2_b32 v[32:33], v128 offset0:160 offset1:176
	v_lshlrev_b64 v[34:35], 12, v[176:177]
	s_waitcnt lgkmcnt(0)
	v_pk_mul_f32 v[36:37], v[30:31], v[32:33] op_sel_hi:[1,0]
	v_pk_mul_f32 v[38:39], v[28:29], v[32:33] op_sel_hi:[1,0]
	v_mov_b64_e32 v[28:29], v[140:141]
	v_mov_b64_e32 v[30:31], v[142:143]
	v_pk_mul_f32 v[30:31], v[30:31], v[36:37]
	v_pk_mul_f32 v[28:29], v[28:29], v[38:39]
	s_nop 0
	v_cvt_pk_bf16_f32 v28, v28, v29
	v_cvt_pk_bf16_f32 v29, v30, v31
	v_lshl_add_u64 v[30:31], s[4:5], 0, v[34:35]
	v_lshl_add_u64 v[30:31], v[30:31], 0, v[126:127]
	global_store_dwordx2 v[30:31], v[28:29], off
	v_pk_mul_f32 v[28:29], v[26:27], v[32:33] op_sel_hi:[1,0]
	v_pk_mul_f32 v[34:35], v[24:25], v[32:33] op_sel_hi:[1,0]
	v_mov_b64_e32 v[24:25], v[144:145]
	v_mov_b64_e32 v[26:27], v[146:147]
	v_pk_mul_f32 v[26:27], v[28:29], v[26:27]
	v_pk_mul_f32 v[24:25], v[34:35], v[24:25]
	s_nop 0
	v_cvt_pk_bf16_f32 v24, v24, v25
	v_cvt_pk_bf16_f32 v25, v26, v27
	global_store_dwordx2 v[30:31], v[24:25], off offset:32
	v_pk_mul_f32 v[24:25], v[22:23], v[32:33] op_sel_hi:[1,0]
	v_pk_mul_f32 v[26:27], v[20:21], v[32:33] op_sel_hi:[1,0]
	v_mov_b64_e32 v[20:21], v[148:149]
	v_mov_b64_e32 v[22:23], v[150:151]
	v_pk_mul_f32 v[22:23], v[24:25], v[22:23]
	v_pk_mul_f32 v[20:21], v[26:27], v[20:21]
	s_nop 0
	v_cvt_pk_bf16_f32 v20, v20, v21
	v_cvt_pk_bf16_f32 v21, v22, v23
	global_store_dwordx2 v[30:31], v[20:21], off offset:256
	v_pk_mul_f32 v[20:21], v[18:19], v[32:33] op_sel_hi:[1,0]
	v_pk_mul_f32 v[22:23], v[16:17], v[32:33] op_sel_hi:[1,0]
	v_mov_b64_e32 v[16:17], v[152:153]
	v_mov_b64_e32 v[18:19], v[154:155]
	v_pk_mul_f32 v[18:19], v[20:21], v[18:19]
	v_pk_mul_f32 v[16:17], v[22:23], v[16:17]
	s_nop 0
	v_cvt_pk_bf16_f32 v16, v16, v17
	v_cvt_pk_bf16_f32 v17, v18, v19
	global_store_dwordx2 v[30:31], v[16:17], off offset:288
	v_mov_b32_e32 v18, v33
	v_pk_mul_f32 v[20:21], v[14:15], v[18:19] op_sel_hi:[1,0]
	v_pk_mul_f32 v[22:23], v[12:13], v[18:19] op_sel_hi:[1,0]
	v_mov_b64_e32 v[12:13], v[140:141]
	v_mov_b64_e32 v[14:15], v[142:143]
	v_lshlrev_b64 v[16:17], 12, v[160:161]
	v_pk_mul_f32 v[14:15], v[14:15], v[20:21]
	v_pk_mul_f32 v[12:13], v[12:13], v[22:23]
	s_nop 0
	v_cvt_pk_bf16_f32 v12, v12, v13
	v_cvt_pk_bf16_f32 v13, v14, v15
	v_lshl_add_u64 v[14:15], s[4:5], 0, v[16:17]
	v_lshl_add_u64 v[14:15], v[14:15], 0, v[126:127]
	global_store_dwordx2 v[14:15], v[12:13], off
	v_pk_mul_f32 v[12:13], v[10:11], v[18:19] op_sel_hi:[1,0]
	v_pk_mul_f32 v[16:17], v[8:9], v[18:19] op_sel_hi:[1,0]
	v_mov_b64_e32 v[8:9], v[144:145]
	v_mov_b64_e32 v[10:11], v[146:147]
	v_pk_mul_f32 v[10:11], v[12:13], v[10:11]
	v_pk_mul_f32 v[8:9], v[16:17], v[8:9]
	s_nop 0
	v_cvt_pk_bf16_f32 v8, v8, v9
	v_cvt_pk_bf16_f32 v9, v10, v11
	global_store_dwordx2 v[14:15], v[8:9], off offset:32
	v_pk_mul_f32 v[8:9], v[6:7], v[18:19] op_sel_hi:[1,0]
	v_pk_mul_f32 v[10:11], v[4:5], v[18:19] op_sel_hi:[1,0]
	v_mov_b64_e32 v[4:5], v[148:149]
	v_mov_b64_e32 v[6:7], v[150:151]
	v_pk_mul_f32 v[6:7], v[8:9], v[6:7]
	v_pk_mul_f32 v[4:5], v[10:11], v[4:5]
	s_nop 0
	v_cvt_pk_bf16_f32 v4, v4, v5
	v_cvt_pk_bf16_f32 v5, v6, v7
	global_store_dwordx2 v[14:15], v[4:5], off offset:256
	v_pk_mul_f32 v[4:5], v[2:3], v[18:19] op_sel_hi:[1,0]
	v_pk_mul_f32 v[6:7], v[0:1], v[18:19] op_sel_hi:[1,0]
	v_mov_b64_e32 v[0:1], v[152:153]
	v_mov_b64_e32 v[2:3], v[154:155]
	v_pk_mul_f32 v[2:3], v[4:5], v[2:3]
	v_pk_mul_f32 v[0:1], v[6:7], v[0:1]
	s_nop 0
	v_cvt_pk_bf16_f32 v0, v0, v1
	v_cvt_pk_bf16_f32 v1, v2, v3
	global_store_dwordx2 v[14:15], v[0:1], off offset:288
